# nt hint on the residual-GEMM epilogue X stores (big tiles), on top of v17
# speedup vs baseline: 1.0044x; 1.0025x over previous
.LBB0_209:
	s_mov_b32 s2, 0xfffd6b00
	s_mov_b32 s3, -1
	v_lshl_add_u64 v[4:5], v[0:1], 0, s[2:3]
	s_mov_b32 s2, 0xfffd9700
	s_mov_b32 s3, -1
	v_lshl_add_u64 v[12:13], v[0:1], 0, s[2:3]
	s_mov_b32 s2, 0xfffdc300
	s_mov_b32 s3, -1
	v_lshl_add_u64 v[14:15], v[0:1], 0, s[2:3]
	s_mov_b32 s2, 0xfffdef00
	s_mov_b32 s3, -1
	v_lshl_add_u64 v[34:35], v[0:1], 0, s[2:3]
	s_mov_b32 s2, 0xfffe1b00
	s_mov_b32 s3, -1
	v_lshl_add_u64 v[36:37], v[0:1], 0, s[2:3]
	s_mov_b32 s2, 0xfffe4700
	s_mov_b32 s3, -1
	v_lshl_add_u64 v[38:39], v[0:1], 0, s[2:3]
	s_mov_b32 s2, 0xfffe7300
	s_mov_b32 s3, -1
	v_lshl_add_u64 v[40:41], v[0:1], 0, s[2:3]
	s_mov_b32 s2, 0xfffe9f00
	s_mov_b32 s3, -1
	v_lshl_add_u64 v[42:43], v[0:1], 0, s[2:3]
	s_mov_b32 s2, 0xfffecb00
	s_mov_b32 s3, -1
	v_lshl_add_u64 v[44:45], v[0:1], 0, s[2:3]
	s_mov_b32 s2, 0xfffef700
	s_mov_b32 s3, -1
	v_lshl_add_u64 v[46:47], v[0:1], 0, s[2:3]
	s_mov_b32 s2, 0xffff2300
	s_mov_b32 s3, -1
	v_lshl_add_u64 v[48:49], v[0:1], 0, s[2:3]
	s_mov_b32 s2, 0xffff4f00
	s_mov_b32 s3, -1
	v_lshl_add_u64 v[50:51], v[0:1], 0, s[2:3]
	s_mov_b32 s2, 0xffff7b00
	s_mov_b32 s3, -1
	v_lshl_add_u64 v[52:53], v[0:1], 0, s[2:3]
	s_movk_i32 s2, 0xa700
	s_mov_b32 s3, -1
	v_lshl_add_u64 v[54:55], v[0:1], 0, s[2:3]
	s_movk_i32 s2, 0xd300
	s_mov_b32 s3, -1
	v_lshl_add_u64 v[56:57], v[0:1], 0, s[2:3]
	s_add_i32 s20, s39, 16
	s_mov_b64 s[2:3], 0x2c000
	global_store_dword v[4:5], v6, off nt
	global_store_dword v[12:13], v7, off nt
	global_store_dword v[14:15], v8, off nt
	global_store_dword v[34:35], v9, off nt
	global_store_dword v[36:37], v20, off nt
	global_store_dword v[38:39], v24, off nt
	global_store_dword v[40:41], v27, off nt
	global_store_dword v[42:43], v30, off nt
	global_store_dword v[44:45], v32, off nt
	global_store_dword v[46:47], v29, off nt
	global_store_dword v[48:49], v26, off nt
	global_store_dword v[50:51], v23, off nt
	global_store_dword v[52:53], v21, off nt
	global_store_dword v[54:55], v18, off nt
	global_store_dword v[56:57], v16, off nt
	global_store_dword v[0:1], v2, off offset:-256 nt
	v_lshl_add_u64 v[0:1], v[0:1], 0, s[2:3]
	s_cmpk_gt_u32 s39, 0x6f
	s_mov_b32 s39, s20
	s_cbranch_scc1 .LBB0_202

.Lup_epi:
	s_lshl_b32 s0, s67, 8
	s_add_i32 s0, s0, s19
	v_add_u32_e32 v134, s0, v182
	v_mov_b32_e32 v141, v182
	s_lshl_b32 s1, s90, 8
	v_add_lshl_u32 v138, v168, s1, 1
	v_mov_b32_e32 v139, 0
	v_mov_b32_e32 v136, 0x2c00
	v_mad_u64_u32 v[144:145], vcc, v134, v136, s[44:45]
	v_lshl_add_u64 v[144:145], v[138:139], 0, v[144:145]
	s_mov_b32 s0, 0x160000
	s_mov_b32 s1, 0
	v_lshl_add_u64 v[146:147], v[144:145], 0, s[0:1]
	s_mov_b32 s0, 0x2c000
	v_cvt_pk_bf16_f32 v224, v128, v129
	v_cvt_pk_bf16_f32 v225, v130, v131
	v_cvt_pk_bf16_f32 v226, v124, v125
	v_cvt_pk_bf16_f32 v227, v126, v127
	global_store_dwordx4 v[144:145], v[224:227], off nt
	v_cvt_pk_bf16_f32 v228, v120, v121
	v_cvt_pk_bf16_f32 v229, v122, v123
	v_cvt_pk_bf16_f32 v230, v116, v117
	v_cvt_pk_bf16_f32 v231, v118, v119
	global_store_dwordx4 v[144:145], v[228:231], off offset:256 nt
	v_cvt_pk_bf16_f32 v232, v60, v61
	v_cvt_pk_bf16_f32 v233, v62, v63
	v_cvt_pk_bf16_f32 v234, v56, v57
	v_cvt_pk_bf16_f32 v235, v58, v59
	global_store_dwordx4 v[146:147], v[232:235], off nt
	v_cvt_pk_bf16_f32 v236, v52, v53
	v_cvt_pk_bf16_f32 v237, v54, v55
	v_cvt_pk_bf16_f32 v238, v48, v49
	v_cvt_pk_bf16_f32 v239, v50, v51
	global_store_dwordx4 v[146:147], v[236:239], off offset:256 nt
	v_lshl_add_u64 v[144:145], v[144:145], 0, s[0:1]
	v_lshl_add_u64 v[146:147], v[146:147], 0, s[0:1]
	v_cvt_pk_bf16_f32 v240, v112, v113
	v_cvt_pk_bf16_f32 v241, v114, v115
	v_cvt_pk_bf16_f32 v242, v108, v109
	v_cvt_pk_bf16_f32 v243, v110, v111
	global_store_dwordx4 v[144:145], v[240:243], off nt
	v_cvt_pk_bf16_f32 v244, v104, v105
	v_cvt_pk_bf16_f32 v245, v106, v107
	v_cvt_pk_bf16_f32 v246, v100, v101
	v_cvt_pk_bf16_f32 v247, v102, v103
	global_store_dwordx4 v[144:145], v[244:247], off offset:256 nt
	v_cvt_pk_bf16_f32 v224, v44, v45
	v_cvt_pk_bf16_f32 v225, v46, v47
	v_cvt_pk_bf16_f32 v226, v40, v41
	v_cvt_pk_bf16_f32 v227, v42, v43
	global_store_dwordx4 v[146:147], v[224:227], off nt
	v_cvt_pk_bf16_f32 v228, v36, v37
	v_cvt_pk_bf16_f32 v229, v38, v39
	v_cvt_pk_bf16_f32 v230, v32, v33
	v_cvt_pk_bf16_f32 v231, v34, v35
	global_store_dwordx4 v[146:147], v[228:231], off offset:256 nt
	v_lshl_add_u64 v[144:145], v[144:145], 0, s[0:1]
	v_lshl_add_u64 v[146:147], v[146:147], 0, s[0:1]
	v_cvt_pk_bf16_f32 v232, v92, v93
	v_cvt_pk_bf16_f32 v233, v94, v95
	v_cvt_pk_bf16_f32 v234, v88, v89
	v_cvt_pk_bf16_f32 v235, v90, v91
	global_store_dwordx4 v[144:145], v[232:235], off nt
	v_cvt_pk_bf16_f32 v236, v84, v85
	v_cvt_pk_bf16_f32 v237, v86, v87
	v_cvt_pk_bf16_f32 v238, v80, v81
	v_cvt_pk_bf16_f32 v239, v82, v83
	global_store_dwordx4 v[144:145], v[236:239], off offset:256 nt
	v_cvt_pk_bf16_f32 v240, v28, v29
	v_cvt_pk_bf16_f32 v241, v30, v31
	v_cvt_pk_bf16_f32 v242, v24, v25
	v_cvt_pk_bf16_f32 v243, v26, v27
	global_store_dwordx4 v[146:147], v[240:243], off nt
	v_cvt_pk_bf16_f32 v244, v20, v21
	v_cvt_pk_bf16_f32 v245, v22, v23
	v_cvt_pk_bf16_f32 v246, v16, v17
	v_cvt_pk_bf16_f32 v247, v18, v19
	global_store_dwordx4 v[146:147], v[244:247], off offset:256 nt
	v_lshl_add_u64 v[144:145], v[144:145], 0, s[0:1]
	v_lshl_add_u64 v[146:147], v[146:147], 0, s[0:1]
	v_cvt_pk_bf16_f32 v170, v76, v77
	v_cvt_pk_bf16_f32 v171, v78, v79
	v_cvt_pk_bf16_f32 v172, v72, v73
	v_cvt_pk_bf16_f32 v173, v74, v75
	global_store_dwordx4 v[144:145], v[170:173], off nt
	v_cvt_pk_bf16_f32 v174, v68, v69
	v_cvt_pk_bf16_f32 v175, v70, v71
	v_cvt_pk_bf16_f32 v176, v64, v65
	v_cvt_pk_bf16_f32 v177, v66, v67
	global_store_dwordx4 v[144:145], v[174:177], off offset:256 nt
	v_cvt_pk_bf16_f32 v188, v12, v13
	v_cvt_pk_bf16_f32 v189, v14, v15
	v_cvt_pk_bf16_f32 v190, v8, v9
	v_cvt_pk_bf16_f32 v191, v10, v11
	global_store_dwordx4 v[146:147], v[188:191], off nt
	v_cvt_pk_bf16_f32 v200, v4, v5
	v_cvt_pk_bf16_f32 v201, v6, v7
	v_cvt_pk_bf16_f32 v202, v0, v1
	v_cvt_pk_bf16_f32 v203, v2, v3
	global_store_dwordx4 v[146:147], v[200:203], off offset:256 nt
	s_cmp_lg_u32 s19, 64
	s_cbranch_scc1 .Lup_done
	v_cmp_lt_u32_e64 s[6:7], 13, v141
	s_and_saveexec_b64 s[16:17], s[6:7]
	s_cbranch_execz .Lup_hdone
	s_lshl_b32 s4, s67, 2
	s_add_i32 s4, s4, -14
	v_add_u32_e32 v140, s4, v141
	s_add_u32 s4, s68, 0x19b0000
	s_addc_u32 s5, s69, 0
	v_mad_u64_u32 v[148:149], vcc, v140, v136, s[4:5]
	v_lshl_add_u64 v[148:149], v[138:139], 0, v[148:149]
	s_mov_b32 s4, 0x5800
	s_mov_b32 s5, 0
	v_lshl_add_u64 v[150:151], v[148:149], 0, s[4:5]
	global_store_dwordx4 v[148:149], v[170:173], off nt
	global_store_dwordx4 v[148:149], v[174:177], off offset:256 nt
	global_store_dwordx4 v[150:151], v[188:191], off nt
	global_store_dwordx4 v[150:151], v[200:203], off offset:256 nt

.LBB0_892:
	v_or_b32_e32 v98, s19, v182
	v_ashrrev_i32_e32 v169, 31, v168
	s_lshl_b32 s0, s90, 8
	v_lshlrev_b64 v[200:201], 1, v[168:169]
	v_lshl_add_u32 v170, s67, 8, v98
	s_ashr_i32 s1, s0, 31
	v_lshl_add_u64 v[132:133], s[44:45], 0, v[200:201]
	s_lshl_b64 s[6:7], s[0:1], 1
	v_ashrrev_i32_e32 v171, 31, v170
	v_or_b32_e32 v180, 16, v170
	v_lshl_add_u64 v[172:173], v[132:133], 0, s[6:7]
	v_lshlrev_b64 v[202:203], 11, v[170:171]
	v_ashrrev_i32_e32 v181, 31, v180
	v_or_b32_e32 v176, 32, v170
	v_lshl_add_u64 v[132:133], v[172:173], 0, v[202:203]
	v_lshlrev_b64 v[184:185], 11, v[180:181]
	v_ashrrev_i32_e32 v177, 31, v176
	v_or_b32_e32 v174, 48, v170
	global_load_dwordx4 v[188:191], v[132:133], off
	global_load_dwordx4 v[196:199], v[132:133], off offset:256
	v_lshl_add_u64 v[132:133], v[172:173], 0, v[184:185]
	v_lshlrev_b64 v[182:183], 11, v[176:177]
	v_ashrrev_i32_e32 v175, 31, v174
	global_load_dwordx4 v[152:155], v[132:133], off
	global_load_dwordx4 v[148:151], v[132:133], off offset:256
	v_lshl_add_u64 v[132:133], v[172:173], 0, v[182:183]
	v_lshlrev_b64 v[178:179], 11, v[174:175]
	global_load_dwordx4 v[144:147], v[132:133], off
	global_load_dwordx4 v[140:143], v[132:133], off offset:256
	v_lshl_add_u64 v[132:133], v[172:173], 0, v[178:179]
	global_load_dwordx4 v[136:139], v[132:133], off
	s_nop 0
	global_load_dwordx4 v[132:135], v[132:133], off offset:256
	v_lshl_add_u64 v[202:203], s[44:45], 0, v[202:203]
	v_lshl_add_u64 v[202:203], v[202:203], 0, s[6:7]
	v_lshl_add_u64 v[200:201], v[202:203], 0, v[200:201]
	v_cmp_gt_i32_e64 s[4:5], 2, v166
	v_cmp_gt_u32_e32 vcc, 16, v167
	v_ashrrev_i32_e32 v167, 31, v166
	s_waitcnt vmcnt(0)
	s_nop 0
	v_lshlrev_b32_e32 v202, 16, v188
	v_and_b32_e32 v203, 0xffff0000, v188
	v_lshlrev_b32_e32 v188, 16, v189
	v_and_b32_e32 v189, 0xffff0000, v189
	v_lshlrev_b32_e32 v204, 16, v190
	v_and_b32_e32 v205, 0xffff0000, v190
	v_lshlrev_b32_e32 v190, 16, v191
	v_and_b32_e32 v191, 0xffff0000, v191
	v_pk_add_f32 v[130:131], v[130:131], v[188:189]
	v_pk_add_f32 v[128:129], v[128:129], v[202:203]
	v_pk_add_f32 v[188:189], v[126:127], v[190:191]
	v_pk_add_f32 v[126:127], v[124:125], v[204:205]
	v_mul_f32_e32 v98, v129, v129
	v_mul_f32_e32 v124, v131, v131
	v_fmac_f32_e32 v98, v128, v128
	v_fmac_f32_e32 v124, v130, v130
	v_add_f32_e32 v98, v98, v124
	v_mul_f32_e32 v124, v127, v127
	v_fmac_f32_e32 v124, v126, v126
	v_add_f32_e32 v98, v124, v98
	v_mul_f32_e32 v124, v189, v189
	v_fmac_f32_e32 v124, v188, v188
	v_add_f32_e32 v98, v124, v98
	v_cvt_pk_bf16_f32 v124, v128, v129
	v_cvt_pk_bf16_f32 v125, v130, v131
	v_cvt_pk_bf16_f32 v126, v126, v127
	v_cvt_pk_bf16_f32 v127, v188, v189
	global_store_dwordx4 v[200:201], v[124:127], off nt
	v_lshlrev_b32_e32 v128, 16, v198
	v_and_b32_e32 v129, 0xffff0000, v198
	v_lshlrev_b32_e32 v124, 16, v196
	v_and_b32_e32 v125, 0xffff0000, v196
	v_lshlrev_b32_e32 v126, 16, v197
	v_and_b32_e32 v127, 0xffff0000, v197
	v_lshlrev_b32_e32 v130, 16, v199
	v_and_b32_e32 v131, 0xffff0000, v199
	v_pk_add_f32 v[122:123], v[122:123], v[126:127]
	v_pk_add_f32 v[120:121], v[120:121], v[124:125]
	v_pk_add_f32 v[124:125], v[118:119], v[130:131]
	v_pk_add_f32 v[118:119], v[116:117], v[128:129]
	v_mul_f32_e32 v116, v121, v121
	v_mul_f32_e32 v117, v123, v123
	v_fmac_f32_e32 v116, v120, v120
	v_fmac_f32_e32 v117, v122, v122
	v_add_f32_e32 v116, v116, v117
	v_mul_f32_e32 v117, v119, v119
	v_fmac_f32_e32 v117, v118, v118
	v_add_f32_e32 v116, v117, v116
	v_mul_f32_e32 v117, v125, v125
	v_fmac_f32_e32 v117, v124, v124
	v_add_f32_e32 v116, v117, v116
	v_add_f32_e32 v126, v98, v116
	v_cvt_pk_bf16_f32 v116, v120, v121
	v_cvt_pk_bf16_f32 v117, v122, v123
	v_cvt_pk_bf16_f32 v118, v118, v119
	v_cvt_pk_bf16_f32 v119, v124, v125
	global_store_dwordx4 v[200:201], v[116:119], off offset:256 nt
	v_xor_b32_e32 v98, 16, v214
	s_nop 0
	v_and_b32_e32 v116, 64, v214
	v_add_u32_e32 v116, 64, v116
	v_cmp_lt_i32_e64 s[6:7], v98, v116
	v_xor_b32_e32 v118, 32, v214
	s_nop 0
	v_cndmask_b32_e64 v98, v214, v98, s[6:7]
	v_lshlrev_b32_e32 v98, 2, v98
	ds_bpermute_b32 v117, v98, v126
	v_cmp_lt_i32_e64 s[6:7], v118, v116
	s_waitcnt lgkmcnt(0)
	v_add_f32_e32 v117, v126, v117
	v_cndmask_b32_e64 v116, v214, v118, s[6:7]
	v_lshlrev_b32_e32 v116, 2, v116
	ds_bpermute_b32 v118, v116, v117
	s_and_saveexec_b64 s[6:7], s[4:5]
	s_cbranch_execz .LBB0_894
	s_waitcnt lgkmcnt(0)
	v_add_f32_e32 v117, v117, v118
	s_lshl_b32 s16, s90, 3
	v_lshlrev_b64 v[118:119], 7, v[170:171]
	s_ashr_i32 s17, s16, 31
	v_lshl_add_u64 v[118:119], s[42:43], 0, v[118:119]
	v_lshl_add_u64 v[118:119], s[16:17], 2, v[118:119]
	s_lshl_b32 s52, s91, 2
	v_lshl_add_u64 v[118:119], v[118:119], 0, s[52:53]
	v_cndmask_b32_e32 v117, 0, v117, vcc
	v_lshl_add_u64 v[118:119], v[166:167], 2, v[118:119]
	global_store_dword v[118:119], v117, off
.LBB0_894:
	s_or_b64 exec, exec, s[6:7]
	v_lshlrev_b32_e32 v120, 16, v152
	v_and_b32_e32 v121, 0xffff0000, v152
	v_lshlrev_b32_e32 v122, 16, v153
	v_and_b32_e32 v123, 0xffff0000, v153
	v_lshlrev_b32_e32 v124, 16, v154
	v_and_b32_e32 v125, 0xffff0000, v154
	v_lshlrev_b32_e32 v126, 16, v155
	v_and_b32_e32 v127, 0xffff0000, v155
	v_pk_add_f32 v[114:115], v[114:115], v[122:123]
	v_pk_add_f32 v[112:113], v[112:113], v[120:121]
	v_pk_add_f32 v[120:121], v[110:111], v[126:127]
	v_pk_add_f32 v[110:111], v[108:109], v[124:125]
	v_mul_f32_e32 v108, v113, v113
	v_mul_f32_e32 v109, v115, v115
	v_fmac_f32_e32 v108, v112, v112
	v_fmac_f32_e32 v109, v114, v114
	v_add_f32_e32 v108, v108, v109
	v_mul_f32_e32 v109, v111, v111
	v_fmac_f32_e32 v109, v110, v110
	v_add_f32_e32 v108, v109, v108
	v_mul_f32_e32 v109, v121, v121
	v_fmac_f32_e32 v109, v120, v120
	v_add_f32_e32 v117, v109, v108
	v_cvt_pk_bf16_f32 v108, v112, v113
	v_cvt_pk_bf16_f32 v109, v114, v115
	v_lshlrev_b32_e32 v112, 16, v148
	v_and_b32_e32 v113, 0xffff0000, v148
	v_lshlrev_b32_e32 v114, 16, v149
	v_and_b32_e32 v115, 0xffff0000, v149
	v_lshlrev_b32_e32 v122, 16, v150
	v_and_b32_e32 v123, 0xffff0000, v150
	v_pk_add_f32 v[106:107], v[106:107], v[114:115]
	v_pk_add_f32 v[104:105], v[104:105], v[112:113]
	v_pk_add_f32 v[114:115], v[100:101], v[122:123]
	v_mul_f32_e32 v100, v105, v105
	v_mul_f32_e32 v101, v107, v107
	v_fmac_f32_e32 v100, v104, v104
	v_fmac_f32_e32 v101, v106, v106
	v_lshlrev_b32_e32 v124, 16, v151
	v_and_b32_e32 v125, 0xffff0000, v151
	v_add_f32_e32 v100, v100, v101
	v_mul_f32_e32 v101, v115, v115
	v_pk_add_f32 v[112:113], v[102:103], v[124:125]
	v_fmac_f32_e32 v101, v114, v114
	v_add_f32_e32 v100, v101, v100
	v_mul_f32_e32 v101, v113, v113
	v_fmac_f32_e32 v101, v112, v112
	v_add_f32_e32 v100, v101, v100
	v_add_f32_e32 v100, v117, v100
	ds_bpermute_b32 v101, v98, v100
	s_waitcnt lgkmcnt(0)
	v_lshl_add_u64 v[118:119], s[44:45], 0, v[184:185]
	v_lshl_add_u64 v[118:119], s[0:1], 1, v[118:119]
	v_lshl_add_u64 v[118:119], v[168:169], 1, v[118:119]
	v_cvt_pk_bf16_f32 v110, v110, v111
	v_add_f32_e32 v100, v100, v101
	ds_bpermute_b32 v101, v116, v100
	v_cvt_pk_bf16_f32 v111, v120, v121
	global_store_dwordx4 v[118:119], v[108:111], off nt
	v_cvt_pk_bf16_f32 v102, v104, v105
	v_cvt_pk_bf16_f32 v103, v106, v107
	v_cvt_pk_bf16_f32 v104, v114, v115
	v_cvt_pk_bf16_f32 v105, v112, v113
	global_store_dwordx4 v[118:119], v[102:105], off offset:256 nt
	s_and_saveexec_b64 s[6:7], s[4:5]
	s_cbranch_execz .LBB0_896
	s_waitcnt lgkmcnt(0)
	v_add_f32_e32 v100, v100, v101
	v_cndmask_b32_e32 v102, 0, v100, vcc
	s_lshl_b32 s16, s90, 3
	v_lshlrev_b64 v[100:101], 7, v[180:181]
	s_ashr_i32 s17, s16, 31
	v_lshl_add_u64 v[100:101], s[42:43], 0, v[100:101]
	v_lshl_add_u64 v[100:101], s[16:17], 2, v[100:101]
	s_lshl_b32 s52, s91, 2
	v_lshl_add_u64 v[100:101], v[100:101], 0, s[52:53]
	v_lshl_add_u64 v[100:101], v[166:167], 2, v[100:101]
	global_store_dword v[100:101], v102, off
.LBB0_896:
	s_or_b64 exec, exec, s[6:7]
	v_lshlrev_b32_e32 v102, 16, v144
	v_and_b32_e32 v103, 0xffff0000, v144
	v_lshlrev_b32_e32 v104, 16, v145
	v_and_b32_e32 v105, 0xffff0000, v145
	v_lshlrev_b32_e32 v106, 16, v146
	v_and_b32_e32 v107, 0xffff0000, v146
	v_lshlrev_b32_e32 v108, 16, v147
	v_and_b32_e32 v109, 0xffff0000, v147
	v_pk_add_f32 v[94:95], v[94:95], v[104:105]
	v_pk_add_f32 v[92:93], v[92:93], v[102:103]
	v_pk_add_f32 v[102:103], v[90:91], v[108:109]
	v_pk_add_f32 v[90:91], v[88:89], v[106:107]
	v_mul_f32_e32 v88, v93, v93
	v_mul_f32_e32 v89, v95, v95
	v_fmac_f32_e32 v88, v92, v92
	v_fmac_f32_e32 v89, v94, v94
	v_add_f32_e32 v88, v88, v89
	v_mul_f32_e32 v89, v91, v91
	v_fmac_f32_e32 v89, v90, v90
	v_add_f32_e32 v88, v89, v88
	v_mul_f32_e32 v89, v103, v103
	v_fmac_f32_e32 v89, v102, v102
	v_add_f32_e32 v108, v89, v88
	v_cvt_pk_bf16_f32 v88, v92, v93
	v_cvt_pk_bf16_f32 v89, v94, v95
	v_lshlrev_b32_e32 v92, 16, v140
	v_and_b32_e32 v93, 0xffff0000, v140
	v_lshlrev_b32_e32 v94, 16, v141
	v_and_b32_e32 v95, 0xffff0000, v141
	v_lshlrev_b32_e32 v104, 16, v142
	v_and_b32_e32 v105, 0xffff0000, v142
	v_pk_add_f32 v[86:87], v[86:87], v[94:95]
	v_pk_add_f32 v[84:85], v[84:85], v[92:93]
	v_pk_add_f32 v[94:95], v[80:81], v[104:105]
	v_mul_f32_e32 v80, v85, v85
	v_mul_f32_e32 v81, v87, v87
	v_fmac_f32_e32 v80, v84, v84
	v_fmac_f32_e32 v81, v86, v86
	v_lshlrev_b32_e32 v106, 16, v143
	v_and_b32_e32 v107, 0xffff0000, v143
	v_add_f32_e32 v80, v80, v81
	v_mul_f32_e32 v81, v95, v95
	v_pk_add_f32 v[92:93], v[82:83], v[106:107]
	v_fmac_f32_e32 v81, v94, v94
	v_add_f32_e32 v80, v81, v80
	v_mul_f32_e32 v81, v93, v93
	v_fmac_f32_e32 v81, v92, v92
	v_add_f32_e32 v80, v81, v80
	v_add_f32_e32 v80, v108, v80
	ds_bpermute_b32 v81, v98, v80
	s_waitcnt lgkmcnt(0)
	v_lshl_add_u64 v[100:101], s[44:45], 0, v[182:183]
	v_lshl_add_u64 v[100:101], s[0:1], 1, v[100:101]
	v_lshl_add_u64 v[100:101], v[168:169], 1, v[100:101]
	v_cvt_pk_bf16_f32 v90, v90, v91
	v_add_f32_e32 v80, v80, v81
	ds_bpermute_b32 v81, v116, v80
	v_cvt_pk_bf16_f32 v91, v102, v103
	global_store_dwordx4 v[100:101], v[88:91], off nt
	v_cvt_pk_bf16_f32 v82, v84, v85
	v_cvt_pk_bf16_f32 v83, v86, v87
	v_cvt_pk_bf16_f32 v84, v94, v95
	v_cvt_pk_bf16_f32 v85, v92, v93
	global_store_dwordx4 v[100:101], v[82:85], off offset:256 nt
	s_and_saveexec_b64 s[6:7], s[4:5]
	s_cbranch_execz .LBB0_898
	s_waitcnt lgkmcnt(0)
	v_add_f32_e32 v80, v80, v81
	v_cndmask_b32_e32 v82, 0, v80, vcc
	s_lshl_b32 s16, s90, 3
	v_lshlrev_b64 v[80:81], 7, v[176:177]
	s_ashr_i32 s17, s16, 31
	v_lshl_add_u64 v[80:81], s[42:43], 0, v[80:81]
	v_lshl_add_u64 v[80:81], s[16:17], 2, v[80:81]
	s_lshl_b32 s52, s91, 2
	v_lshl_add_u64 v[80:81], v[80:81], 0, s[52:53]
	v_lshl_add_u64 v[80:81], v[166:167], 2, v[80:81]
	global_store_dword v[80:81], v82, off
.LBB0_898:
	s_or_b64 exec, exec, s[6:7]
	v_lshlrev_b32_e32 v82, 16, v136
	v_and_b32_e32 v83, 0xffff0000, v136
	v_lshlrev_b32_e32 v84, 16, v137
	v_and_b32_e32 v85, 0xffff0000, v137
	v_lshlrev_b32_e32 v86, 16, v138
	v_and_b32_e32 v87, 0xffff0000, v138
	v_lshlrev_b32_e32 v88, 16, v139
	v_and_b32_e32 v89, 0xffff0000, v139
	v_pk_add_f32 v[78:79], v[78:79], v[84:85]
	v_pk_add_f32 v[76:77], v[76:77], v[82:83]
	v_pk_add_f32 v[82:83], v[74:75], v[88:89]
	v_pk_add_f32 v[74:75], v[72:73], v[86:87]
	v_mul_f32_e32 v72, v77, v77
	v_mul_f32_e32 v73, v79, v79
	v_fmac_f32_e32 v72, v76, v76
	v_fmac_f32_e32 v73, v78, v78
	v_add_f32_e32 v72, v72, v73
	v_mul_f32_e32 v73, v75, v75
	v_fmac_f32_e32 v73, v74, v74
	v_add_f32_e32 v72, v73, v72
	v_mul_f32_e32 v73, v83, v83
	v_fmac_f32_e32 v73, v82, v82
	v_add_f32_e32 v88, v73, v72
	v_cvt_pk_bf16_f32 v72, v76, v77
	v_cvt_pk_bf16_f32 v73, v78, v79
	v_lshlrev_b32_e32 v76, 16, v132
	v_and_b32_e32 v77, 0xffff0000, v132
	v_lshlrev_b32_e32 v78, 16, v133
	v_and_b32_e32 v79, 0xffff0000, v133
	v_lshlrev_b32_e32 v84, 16, v134
	v_and_b32_e32 v85, 0xffff0000, v134
	v_pk_add_f32 v[70:71], v[70:71], v[78:79]
	v_pk_add_f32 v[68:69], v[68:69], v[76:77]
	v_pk_add_f32 v[78:79], v[64:65], v[84:85]
	v_mul_f32_e32 v64, v69, v69
	v_mul_f32_e32 v65, v71, v71
	v_fmac_f32_e32 v64, v68, v68
	v_fmac_f32_e32 v65, v70, v70
	v_lshlrev_b32_e32 v86, 16, v135
	v_and_b32_e32 v87, 0xffff0000, v135
	v_add_f32_e32 v64, v64, v65
	v_mul_f32_e32 v65, v79, v79
	v_pk_add_f32 v[76:77], v[66:67], v[86:87]
	v_fmac_f32_e32 v65, v78, v78
	v_add_f32_e32 v64, v65, v64
	v_mul_f32_e32 v65, v77, v77
	v_fmac_f32_e32 v65, v76, v76
	v_add_f32_e32 v64, v65, v64
	v_add_f32_e32 v64, v88, v64
	ds_bpermute_b32 v65, v98, v64
	s_waitcnt lgkmcnt(0)
	v_lshl_add_u64 v[80:81], s[44:45], 0, v[178:179]
	v_lshl_add_u64 v[80:81], s[0:1], 1, v[80:81]
	v_lshl_add_u64 v[80:81], v[168:169], 1, v[80:81]
	v_cvt_pk_bf16_f32 v74, v74, v75
	v_add_f32_e32 v64, v64, v65
	ds_bpermute_b32 v65, v116, v64
	v_cvt_pk_bf16_f32 v75, v82, v83
	global_store_dwordx4 v[80:81], v[72:75], off nt
	v_cvt_pk_bf16_f32 v66, v68, v69
	v_cvt_pk_bf16_f32 v67, v70, v71
	v_cvt_pk_bf16_f32 v68, v78, v79
	v_cvt_pk_bf16_f32 v69, v76, v77
	global_store_dwordx4 v[80:81], v[66:69], off offset:256 nt
	s_and_saveexec_b64 s[6:7], s[4:5]
	s_cbranch_execz .LBB0_900
	s_waitcnt lgkmcnt(0)
	v_add_f32_e32 v64, v64, v65
	v_cndmask_b32_e32 v66, 0, v64, vcc
	s_lshl_b32 s16, s90, 3
	v_lshlrev_b64 v[64:65], 7, v[174:175]
	s_ashr_i32 s17, s16, 31
	v_lshl_add_u64 v[64:65], s[42:43], 0, v[64:65]
	v_lshl_add_u64 v[64:65], s[16:17], 2, v[64:65]
	s_lshl_b32 s52, s91, 2
	v_lshl_add_u64 v[64:65], v[64:65], 0, s[52:53]
	v_lshl_add_u64 v[64:65], v[166:167], 2, v[64:65]
	global_store_dword v[64:65], v66, off
.LBB0_900:
	s_or_b64 exec, exec, s[6:7]
	v_add_u32_e32 v94, 0x80, v170
	v_ashrrev_i32_e32 v95, 31, v94
	v_add_u32_e32 v92, 0x90, v170
	v_lshlrev_b64 v[102:103], 11, v[94:95]
	v_ashrrev_i32_e32 v93, 31, v92
	s_waitcnt lgkmcnt(0)
	v_lshl_add_u64 v[64:65], v[172:173], 0, v[102:103]
	v_lshlrev_b64 v[100:101], 11, v[92:93]
	v_add_u32_e32 v90, 0xa0, v170
	global_load_dwordx4 v[104:107], v[64:65], off
	global_load_dwordx4 v[108:111], v[64:65], off offset:256
	v_lshl_add_u64 v[64:65], v[172:173], 0, v[100:101]
	v_ashrrev_i32_e32 v91, 31, v90
	global_load_dwordx4 v[84:87], v[64:65], off
	global_load_dwordx4 v[80:83], v[64:65], off offset:256
	v_lshlrev_b64 v[64:65], 11, v[90:91]
	v_add_u32_e32 v88, 0xb0, v170
	v_lshl_add_u64 v[64:65], v[172:173], 0, v[64:65]
	v_ashrrev_i32_e32 v89, 31, v88
	global_load_dwordx4 v[76:79], v[64:65], off
	global_load_dwordx4 v[72:75], v[64:65], off offset:256
	v_lshlrev_b64 v[64:65], 11, v[88:89]
	v_lshl_add_u64 v[64:65], v[172:173], 0, v[64:65]
	global_load_dwordx4 v[68:71], v[64:65], off
	s_nop 0
	global_load_dwordx4 v[64:67], v[64:65], off offset:256
	v_lshl_add_u64 v[102:103], s[44:45], 0, v[102:103]
	v_lshl_add_u64 v[102:103], s[0:1], 1, v[102:103]
	v_lshl_add_u64 v[102:103], v[168:169], 1, v[102:103]
	s_waitcnt vmcnt(0)
	s_nop 0
	v_lshlrev_b32_e32 v112, 16, v104
	v_and_b32_e32 v113, 0xffff0000, v104
	v_lshlrev_b32_e32 v104, 16, v105
	v_and_b32_e32 v105, 0xffff0000, v105
	v_lshlrev_b32_e32 v114, 16, v106
	v_and_b32_e32 v115, 0xffff0000, v106
	v_lshlrev_b32_e32 v106, 16, v107
	v_and_b32_e32 v107, 0xffff0000, v107
	v_pk_add_f32 v[62:63], v[62:63], v[104:105]
	v_pk_add_f32 v[60:61], v[60:61], v[112:113]
	v_pk_add_f32 v[104:105], v[58:59], v[106:107]
	v_pk_add_f32 v[58:59], v[56:57], v[114:115]
	v_mul_f32_e32 v56, v61, v61
	v_mul_f32_e32 v57, v63, v63
	v_fmac_f32_e32 v56, v60, v60
	v_fmac_f32_e32 v57, v62, v62
	v_add_f32_e32 v56, v56, v57
	v_mul_f32_e32 v57, v59, v59
	v_fmac_f32_e32 v57, v58, v58
	v_add_f32_e32 v56, v57, v56
	v_mul_f32_e32 v57, v105, v105
	v_fmac_f32_e32 v57, v104, v104
	v_add_f32_e32 v106, v57, v56
	v_cvt_pk_bf16_f32 v56, v60, v61
	v_cvt_pk_bf16_f32 v57, v62, v63
	v_cvt_pk_bf16_f32 v58, v58, v59
	v_cvt_pk_bf16_f32 v59, v104, v105
	global_store_dwordx4 v[102:103], v[56:59], off nt
	v_lshlrev_b32_e32 v60, 16, v110
	v_and_b32_e32 v61, 0xffff0000, v110
	v_lshlrev_b32_e32 v56, 16, v108
	v_and_b32_e32 v57, 0xffff0000, v108
	v_lshlrev_b32_e32 v58, 16, v109
	v_and_b32_e32 v59, 0xffff0000, v109
	v_lshlrev_b32_e32 v62, 16, v111
	v_and_b32_e32 v63, 0xffff0000, v111
	v_pk_add_f32 v[54:55], v[54:55], v[58:59]
	v_pk_add_f32 v[52:53], v[52:53], v[56:57]
	v_pk_add_f32 v[56:57], v[50:51], v[62:63]
	v_pk_add_f32 v[50:51], v[48:49], v[60:61]
	v_mul_f32_e32 v48, v53, v53
	v_mul_f32_e32 v49, v55, v55
	v_fmac_f32_e32 v48, v52, v52
	v_fmac_f32_e32 v49, v54, v54
	v_add_f32_e32 v48, v48, v49
	v_mul_f32_e32 v49, v51, v51
	v_fmac_f32_e32 v49, v50, v50
	v_add_f32_e32 v48, v49, v48
	v_mul_f32_e32 v49, v57, v57
	v_fmac_f32_e32 v49, v56, v56
	v_add_f32_e32 v48, v49, v48
	v_add_f32_e32 v58, v106, v48
	v_cvt_pk_bf16_f32 v48, v52, v53
	v_cvt_pk_bf16_f32 v49, v54, v55
	v_cvt_pk_bf16_f32 v50, v50, v51
	v_cvt_pk_bf16_f32 v51, v56, v57
	global_store_dwordx4 v[102:103], v[48:51], off offset:256 nt
	ds_bpermute_b32 v48, v98, v58
	s_waitcnt lgkmcnt(0)
	v_add_f32_e32 v48, v58, v48
	ds_bpermute_b32 v49, v116, v48
	s_and_saveexec_b64 s[6:7], s[4:5]
	s_cbranch_execz .LBB0_902
	s_waitcnt lgkmcnt(0)
	v_add_f32_e32 v48, v48, v49
	v_cndmask_b32_e32 v50, 0, v48, vcc
	s_lshl_b32 s16, s90, 3
	v_lshlrev_b64 v[48:49], 7, v[94:95]
	s_ashr_i32 s17, s16, 31
	v_lshl_add_u64 v[48:49], s[42:43], 0, v[48:49]
	v_lshl_add_u64 v[48:49], s[16:17], 2, v[48:49]
	s_lshl_b32 s52, s91, 2
	v_lshl_add_u64 v[48:49], v[48:49], 0, s[52:53]
	v_lshl_add_u64 v[48:49], v[166:167], 2, v[48:49]
	global_store_dword v[48:49], v50, off
.LBB0_902:
	s_or_b64 exec, exec, s[6:7]
	v_lshlrev_b32_e32 v50, 16, v84
	v_and_b32_e32 v51, 0xffff0000, v84
	v_lshlrev_b32_e32 v52, 16, v85
	v_and_b32_e32 v53, 0xffff0000, v85
	v_lshlrev_b32_e32 v54, 16, v86
	v_and_b32_e32 v55, 0xffff0000, v86
	v_lshlrev_b32_e32 v56, 16, v87
	v_and_b32_e32 v57, 0xffff0000, v87
	v_pk_add_f32 v[46:47], v[46:47], v[52:53]
	v_pk_add_f32 v[44:45], v[44:45], v[50:51]
	v_pk_add_f32 v[50:51], v[42:43], v[56:57]
	v_pk_add_f32 v[42:43], v[40:41], v[54:55]
	v_mul_f32_e32 v40, v45, v45
	v_mul_f32_e32 v41, v47, v47
	v_fmac_f32_e32 v40, v44, v44
	v_fmac_f32_e32 v41, v46, v46
	v_add_f32_e32 v40, v40, v41
	v_mul_f32_e32 v41, v43, v43
	v_fmac_f32_e32 v41, v42, v42
	v_add_f32_e32 v40, v41, v40
	v_mul_f32_e32 v41, v51, v51
	v_fmac_f32_e32 v41, v50, v50
	v_add_f32_e32 v56, v41, v40
	v_cvt_pk_bf16_f32 v40, v44, v45
	v_cvt_pk_bf16_f32 v41, v46, v47
	v_lshlrev_b32_e32 v44, 16, v80
	v_and_b32_e32 v45, 0xffff0000, v80
	v_lshlrev_b32_e32 v46, 16, v81
	v_and_b32_e32 v47, 0xffff0000, v81
	v_lshlrev_b32_e32 v52, 16, v82
	v_and_b32_e32 v53, 0xffff0000, v82
	v_pk_add_f32 v[38:39], v[38:39], v[46:47]
	v_pk_add_f32 v[36:37], v[36:37], v[44:45]
	v_pk_add_f32 v[46:47], v[32:33], v[52:53]
	v_mul_f32_e32 v32, v37, v37
	v_mul_f32_e32 v33, v39, v39
	v_fmac_f32_e32 v32, v36, v36
	v_fmac_f32_e32 v33, v38, v38
	v_lshlrev_b32_e32 v54, 16, v83
	v_and_b32_e32 v55, 0xffff0000, v83
	v_add_f32_e32 v32, v32, v33
	v_mul_f32_e32 v33, v47, v47
	v_pk_add_f32 v[44:45], v[34:35], v[54:55]
	v_fmac_f32_e32 v33, v46, v46
	v_add_f32_e32 v32, v33, v32
	v_mul_f32_e32 v33, v45, v45
	v_fmac_f32_e32 v33, v44, v44
	v_add_f32_e32 v32, v33, v32
	v_add_f32_e32 v32, v56, v32
	ds_bpermute_b32 v33, v98, v32
	s_waitcnt lgkmcnt(0)
	v_lshl_add_u64 v[48:49], s[44:45], 0, v[100:101]
	v_lshl_add_u64 v[48:49], s[0:1], 1, v[48:49]
	v_lshl_add_u64 v[48:49], v[168:169], 1, v[48:49]
	v_cvt_pk_bf16_f32 v42, v42, v43
	v_add_f32_e32 v32, v32, v33
	ds_bpermute_b32 v33, v116, v32
	v_cvt_pk_bf16_f32 v43, v50, v51
	global_store_dwordx4 v[48:49], v[40:43], off nt
	v_cvt_pk_bf16_f32 v34, v36, v37
	v_cvt_pk_bf16_f32 v35, v38, v39
	v_cvt_pk_bf16_f32 v36, v46, v47
	v_cvt_pk_bf16_f32 v37, v44, v45
	global_store_dwordx4 v[48:49], v[34:37], off offset:256 nt
	s_and_saveexec_b64 s[6:7], s[4:5]
	s_cbranch_execz .LBB0_904
	s_waitcnt lgkmcnt(0)
	v_add_f32_e32 v32, v32, v33
	v_cndmask_b32_e32 v34, 0, v32, vcc
	s_lshl_b32 s16, s90, 3
	v_lshlrev_b64 v[32:33], 7, v[92:93]
	s_ashr_i32 s17, s16, 31
	v_lshl_add_u64 v[32:33], s[42:43], 0, v[32:33]
	v_lshl_add_u64 v[32:33], s[16:17], 2, v[32:33]
	s_lshl_b32 s52, s91, 2
	v_lshl_add_u64 v[32:33], v[32:33], 0, s[52:53]
	v_lshl_add_u64 v[32:33], v[166:167], 2, v[32:33]
	global_store_dword v[32:33], v34, off
.LBB0_904:
	s_or_b64 exec, exec, s[6:7]
	v_lshlrev_b32_e32 v34, 16, v76
	v_and_b32_e32 v35, 0xffff0000, v76
	v_lshlrev_b32_e32 v36, 16, v77
	v_and_b32_e32 v37, 0xffff0000, v77
	v_lshlrev_b32_e32 v38, 16, v78
	v_and_b32_e32 v39, 0xffff0000, v78
	v_lshlrev_b32_e32 v40, 16, v79
	v_and_b32_e32 v41, 0xffff0000, v79
	v_pk_add_f32 v[30:31], v[30:31], v[36:37]
	v_pk_add_f32 v[28:29], v[28:29], v[34:35]
	v_pk_add_f32 v[34:35], v[26:27], v[40:41]
	v_pk_add_f32 v[26:27], v[24:25], v[38:39]
	v_mul_f32_e32 v24, v29, v29
	v_mul_f32_e32 v25, v31, v31
	v_fmac_f32_e32 v24, v28, v28
	v_fmac_f32_e32 v25, v30, v30
	v_add_f32_e32 v24, v24, v25
	v_mul_f32_e32 v25, v27, v27
	v_fmac_f32_e32 v25, v26, v26
	v_add_f32_e32 v24, v25, v24
	v_mul_f32_e32 v25, v35, v35
	v_fmac_f32_e32 v25, v34, v34
	v_add_f32_e32 v40, v25, v24
	v_cvt_pk_bf16_f32 v24, v28, v29
	v_cvt_pk_bf16_f32 v25, v30, v31
	v_lshlrev_b32_e32 v28, 16, v72
	v_and_b32_e32 v29, 0xffff0000, v72
	v_lshlrev_b32_e32 v30, 16, v73
	v_and_b32_e32 v31, 0xffff0000, v73
	v_lshlrev_b32_e32 v36, 16, v74
	v_and_b32_e32 v37, 0xffff0000, v74
	v_pk_add_f32 v[22:23], v[22:23], v[30:31]
	v_pk_add_f32 v[20:21], v[20:21], v[28:29]
	v_pk_add_f32 v[30:31], v[16:17], v[36:37]
	v_mul_f32_e32 v16, v21, v21
	v_mul_f32_e32 v17, v23, v23
	v_fmac_f32_e32 v16, v20, v20
	v_fmac_f32_e32 v17, v22, v22
	v_lshlrev_b32_e32 v38, 16, v75
	v_and_b32_e32 v39, 0xffff0000, v75
	v_add_f32_e32 v16, v16, v17
	v_mul_f32_e32 v17, v31, v31
	v_pk_add_f32 v[28:29], v[18:19], v[38:39]
	v_fmac_f32_e32 v17, v30, v30
	v_add_f32_e32 v16, v17, v16
	v_mul_f32_e32 v17, v29, v29
	v_fmac_f32_e32 v17, v28, v28
	v_add_f32_e32 v16, v17, v16
	v_add_f32_e32 v16, v40, v16
	ds_bpermute_b32 v17, v98, v16
	s_waitcnt lgkmcnt(0)
	v_lshlrev_b64 v[32:33], 11, v[90:91]
	v_lshl_add_u64 v[32:33], s[44:45], 0, v[32:33]
	v_lshl_add_u64 v[32:33], s[0:1], 1, v[32:33]
	v_lshl_add_u64 v[32:33], v[168:169], 1, v[32:33]
	v_add_f32_e32 v16, v16, v17
	ds_bpermute_b32 v17, v116, v16
	v_cvt_pk_bf16_f32 v26, v26, v27
	v_cvt_pk_bf16_f32 v27, v34, v35
	global_store_dwordx4 v[32:33], v[24:27], off nt
	v_cvt_pk_bf16_f32 v18, v20, v21
	v_cvt_pk_bf16_f32 v19, v22, v23
	v_cvt_pk_bf16_f32 v20, v30, v31
	v_cvt_pk_bf16_f32 v21, v28, v29
	global_store_dwordx4 v[32:33], v[18:21], off offset:256 nt
	s_and_saveexec_b64 s[6:7], s[4:5]
	s_cbranch_execz .LBB0_906
	s_waitcnt lgkmcnt(0)
	v_add_f32_e32 v16, v16, v17
	v_cndmask_b32_e32 v18, 0, v16, vcc
	s_lshl_b32 s16, s90, 3
	v_lshlrev_b64 v[16:17], 7, v[90:91]
	s_ashr_i32 s17, s16, 31
	v_lshl_add_u64 v[16:17], s[42:43], 0, v[16:17]
	v_lshl_add_u64 v[16:17], s[16:17], 2, v[16:17]
	s_lshl_b32 s52, s91, 2
	v_lshl_add_u64 v[16:17], v[16:17], 0, s[52:53]
	v_lshl_add_u64 v[16:17], v[166:167], 2, v[16:17]
	global_store_dword v[16:17], v18, off
.LBB0_906:
	s_or_b64 exec, exec, s[6:7]
	v_lshlrev_b32_e32 v18, 16, v68
	v_and_b32_e32 v19, 0xffff0000, v68
	v_lshlrev_b32_e32 v20, 16, v69
	v_and_b32_e32 v21, 0xffff0000, v69
	v_lshlrev_b32_e32 v22, 16, v70
	v_and_b32_e32 v23, 0xffff0000, v70
	v_lshlrev_b32_e32 v24, 16, v71
	v_and_b32_e32 v25, 0xffff0000, v71
	v_pk_add_f32 v[14:15], v[14:15], v[20:21]
	v_pk_add_f32 v[12:13], v[12:13], v[18:19]
	v_pk_add_f32 v[18:19], v[10:11], v[24:25]
	v_pk_add_f32 v[10:11], v[8:9], v[22:23]
	v_mul_f32_e32 v8, v13, v13
	v_mul_f32_e32 v9, v15, v15
	v_fmac_f32_e32 v8, v12, v12
	v_fmac_f32_e32 v9, v14, v14
	v_add_f32_e32 v8, v8, v9
	v_mul_f32_e32 v9, v11, v11
	v_fmac_f32_e32 v9, v10, v10
	v_add_f32_e32 v8, v9, v8
	v_mul_f32_e32 v9, v19, v19
	v_fmac_f32_e32 v9, v18, v18
	v_add_f32_e32 v24, v9, v8
	v_cvt_pk_bf16_f32 v8, v12, v13
	v_cvt_pk_bf16_f32 v9, v14, v15
	v_lshlrev_b32_e32 v12, 16, v64
	v_and_b32_e32 v13, 0xffff0000, v64
	v_lshlrev_b32_e32 v14, 16, v65
	v_and_b32_e32 v15, 0xffff0000, v65
	v_lshlrev_b32_e32 v20, 16, v66
	v_and_b32_e32 v21, 0xffff0000, v66
	v_pk_add_f32 v[6:7], v[6:7], v[14:15]
	v_pk_add_f32 v[4:5], v[4:5], v[12:13]
	v_pk_add_f32 v[14:15], v[0:1], v[20:21]
	v_mul_f32_e32 v0, v5, v5
	v_mul_f32_e32 v1, v7, v7
	v_fmac_f32_e32 v0, v4, v4
	v_fmac_f32_e32 v1, v6, v6
	v_lshlrev_b32_e32 v22, 16, v67
	v_and_b32_e32 v23, 0xffff0000, v67
	v_add_f32_e32 v0, v0, v1
	v_mul_f32_e32 v1, v15, v15
	v_pk_add_f32 v[12:13], v[2:3], v[22:23]
	v_fmac_f32_e32 v1, v14, v14
	v_add_f32_e32 v0, v1, v0
	v_mul_f32_e32 v1, v13, v13
	v_fmac_f32_e32 v1, v12, v12
	v_add_f32_e32 v0, v1, v0
	v_add_f32_e32 v0, v24, v0
	ds_bpermute_b32 v1, v98, v0
	s_waitcnt lgkmcnt(0)
	v_lshlrev_b64 v[16:17], 11, v[88:89]
	v_lshl_add_u64 v[16:17], s[44:45], 0, v[16:17]
	v_lshl_add_u64 v[16:17], s[0:1], 1, v[16:17]
	v_lshl_add_u64 v[16:17], v[168:169], 1, v[16:17]
	v_add_f32_e32 v0, v0, v1
	ds_bpermute_b32 v1, v116, v0
	v_cvt_pk_bf16_f32 v10, v10, v11
	v_cvt_pk_bf16_f32 v11, v18, v19
	global_store_dwordx4 v[16:17], v[8:11], off nt
	v_cvt_pk_bf16_f32 v2, v4, v5
	v_cvt_pk_bf16_f32 v3, v6, v7
	v_cvt_pk_bf16_f32 v4, v14, v15
	v_cvt_pk_bf16_f32 v5, v12, v13
	global_store_dwordx4 v[16:17], v[2:5], off offset:256 nt
	s_and_saveexec_b64 s[0:1], s[4:5]
	s_cbranch_execz .LBB0_908
	s_waitcnt lgkmcnt(0)
	v_add_f32_e32 v0, v0, v1
	v_cndmask_b32_e32 v2, 0, v0, vcc
	s_lshl_b32 s4, s90, 3
	v_lshlrev_b64 v[0:1], 7, v[88:89]
	s_ashr_i32 s5, s4, 31
	v_lshl_add_u64 v[0:1], s[42:43], 0, v[0:1]
	v_lshl_add_u64 v[0:1], s[4:5], 2, v[0:1]
	s_lshl_b32 s52, s91, 2
	v_lshl_add_u64 v[0:1], v[0:1], 0, s[52:53]
	v_lshl_add_u64 v[0:1], v[166:167], 2, v[0:1]
	global_store_dword v[0:1], v2, off
